# GEMM K-loops issue LDS-DMA loads in scalar-base plus 32-bit offset form (no per-load 64-bit VALU adds); attention PV MFMAs accumulate in place (compiler phi copies removed)
# speedup vs baseline: 1.0047x; 1.0047x over previous
; #define PG8_STAGE(bufoff, gbase, voff) do { _Pragma("unroll") for (int _i = 0; _i < 2; ++_i) \
;         __builtin_amdgcn_global_load_lds((const unsigned*)((const char*)(gbase) + (voff)[_i]), (PG8_LAS unsigned*)(lds + (bufoff) + ldsw + _i * 8192), 16, 0, 0); } while (0)
; #define PG8_LDA(dst, b, h) do { _Pragma("unroll") for (int m = 0; m < 4; ++m) _Pragma("unroll") for (int k = 0; k < 2; ++k) dst[m][k] = *(const PG8_LAS bf16x8*)(lds + PG8_SA(b, h) + aoff + m * 2048 + k * 1024); } while (0)
; #define PG8_LDB(dst, b, h) do { _Pragma("unroll") for (int n = 0; n < 2; ++n) _Pragma("unroll") for (int k = 0; k < 2; ++k) dst[n][k] = *(const PG8_LAS bf16x8*)(lds + PG8_SB(b, h) + boff + n * 2048 + k * 1024); } while (0)
; #define PG8_MMA(ai, bj, At, Bt) do { __builtin_amdgcn_s_setprio(1); _Pragma("unroll") for (int m = 0; m < 4; ++m) _Pragma("unroll") for (int n = 0; n < 2; ++n) _Pragma("unroll") for (int k = 0; k < 2; ++k) \
;         acc[ai][bj][m][n] = __builtin_amdgcn_mfma_f32_16x16x32_bf16(Bt[n][k], At[m][k], acc[ai][bj][m][n], 0, 0, 0); __builtin_amdgcn_s_setprio(0); } while (0)
; #define PG8_WAIT_V(n) asm volatile("s_waitcnt vmcnt(" #n ")" ::: "memory")
; #define PG8_WAIT_L(n) asm volatile("s_waitcnt lgkmcnt(" #n ")" ::: "memory")
; #define PG8_BAR __builtin_amdgcn_s_barrier()
; #define PG8_SCHED __builtin_amdgcn_sched_barrier(0)
; template <class Epi, class Sched, bool ALIGN_EPI = false, bool SP2 = false>
; __device__ __forceinline__ void gemm_phase(PG8_LAS unsigned char* lds, const Sched& S, const Epi& E, int wave_id) {
;     ...
;             PG8_LDB(B0, 0, 0); PG8_LDB(B1, 0, 1); PG8_SCHED; PG8_LDA(At, 0, 0); PG8_STAGE(PG8_SA(1, 1), a1 + hstep, voffA);
;             PG8_WAIT_V(8); PG8_WAIT_L(0); PG8_BAR; PG8_MMA(0, 0, At, B0); PG8_MMA(0, 1, At, B1); PG8_BAR; PG8_SCHED;
;             PG8_LDA(At, 0, 1); PG8_STAGE(PG8_SB(0, 0), b2, voffB); PG8_STAGE(PG8_SB(0, 1), b2 + hstep, voffB); PG8_STAGE(PG8_SA(0, 0), a2, voffA);
;             PG8_WAIT_V(8); PG8_WAIT_L(0); PG8_BAR; PG8_MMA(1, 0, At, B0); PG8_MMA(1, 1, At, B1); PG8_BAR; PG8_SCHED;
.LBB0_89:
	s_add_u32 s20, s38, 0xfff80080
	s_addc_u32 s21, s39, -1
	s_add_i32 s60, 0, 0x10000
	s_cmp_eq_u32 s19, 28
	s_cselect_b32 s45, s29, s21
	s_cselect_b32 s44, s28, s20
	s_cselect_b32 s43, s41, s17
	s_cselect_b32 s42, s40, s16
	s_add_i32 s66, 0, 0x14000
	v_add_u32_e32 v54, s60, v164
	v_add_u32_e32 v174, s66, v164
	ds_read_b128 v[34:37], v54
	ds_read_b128 v[38:41], v54 offset:1024
	ds_read_b128 v[50:53], v54 offset:2048
	ds_read_b128 v[54:57], v54 offset:3072
	ds_read_b128 v[160:163], v174
	ds_read_b128 v[166:169], v174 offset:1024
	ds_read_b128 v[170:173], v174 offset:2048
	ds_read_b128 v[174:177], v174 offset:3072
	s_add_i32 m0, s23, 0xc000
	ds_read_b128 v[178:181], v165
	ds_read_b128 v[182:185], v165 offset:1024
	ds_read_b128 v[186:189], v165 offset:2048
	ds_read_b128 v[190:193], v165 offset:3072
	ds_read_b128 v[196:199], v165 offset:4096
	ds_read_b128 v[200:203], v165 offset:5120
	ds_read_b128 v[204:207], v165 offset:6144
	ds_read_b128 v[208:211], v165 offset:7168
	global_load_lds_dwordx4 v156, s[38:39]
	s_add_i32 m0, s23, 0xe000
	s_nop 0
	global_load_lds_dwordx4 v158, s[38:39]
	s_waitcnt vmcnt(8)
	s_waitcnt lgkmcnt(0)
	s_barrier
	s_setprio 1
	s_waitcnt lgkmcnt(0)
	v_mfma_f32_16x16x32_bf16 v[142:145], v[34:37], v[178:181], v[142:145]
	v_mfma_f32_16x16x32_bf16 v[138:141], v[50:53], v[178:181], v[138:141]
	v_mfma_f32_16x16x32_bf16 v[126:129], v[34:37], v[186:189], v[126:129]
	v_mfma_f32_16x16x32_bf16 v[122:125], v[50:53], v[186:189], v[122:125]
	v_mfma_f32_16x16x32_bf16 v[110:113], v[34:37], v[196:199], v[110:113]
	v_mfma_f32_16x16x32_bf16 v[106:109], v[50:53], v[196:199], v[106:109]
	v_mfma_f32_16x16x32_bf16 v[94:97], v[34:37], v[204:207], v[94:97]
	v_mfma_f32_16x16x32_bf16 v[90:93], v[50:53], v[204:207], v[90:93]
	v_mfma_f32_16x16x32_bf16 v[142:145], v[38:41], v[182:185], v[142:145]
	v_mfma_f32_16x16x32_bf16 v[138:141], v[54:57], v[182:185], v[138:141]
	v_mfma_f32_16x16x32_bf16 v[126:129], v[38:41], v[190:193], v[126:129]
	v_mfma_f32_16x16x32_bf16 v[122:125], v[54:57], v[190:193], v[122:125]
	v_mfma_f32_16x16x32_bf16 v[110:113], v[38:41], v[200:203], v[110:113]
	v_mfma_f32_16x16x32_bf16 v[106:109], v[54:57], v[200:203], v[106:109]
	v_mfma_f32_16x16x32_bf16 v[94:97], v[38:41], v[208:211], v[94:97]
	v_mfma_f32_16x16x32_bf16 v[90:93], v[54:57], v[208:211], v[90:93]
	s_setprio 0
	s_setprio 1
	v_mfma_f32_16x16x32_bf16 v[134:137], v[160:163], v[178:181], v[134:137]
	v_mfma_f32_16x16x32_bf16 v[130:133], v[170:173], v[178:181], v[130:133]
	v_mfma_f32_16x16x32_bf16 v[118:121], v[160:163], v[186:189], v[118:121]
	v_mfma_f32_16x16x32_bf16 v[114:117], v[170:173], v[186:189], v[114:117]
	v_mfma_f32_16x16x32_bf16 v[102:105], v[160:163], v[196:199], v[102:105]
	v_mfma_f32_16x16x32_bf16 v[98:101], v[170:173], v[196:199], v[98:101]
	v_mfma_f32_16x16x32_bf16 v[86:89], v[160:163], v[204:207], v[86:89]
	v_mfma_f32_16x16x32_bf16 v[82:85], v[170:173], v[204:207], v[82:85]
	v_mfma_f32_16x16x32_bf16 v[134:137], v[166:169], v[182:185], v[134:137]
	v_mfma_f32_16x16x32_bf16 v[130:133], v[174:177], v[182:185], v[130:133]
	v_mfma_f32_16x16x32_bf16 v[118:121], v[166:169], v[190:193], v[118:121]
	v_mfma_f32_16x16x32_bf16 v[114:117], v[174:177], v[190:193], v[114:117]
	v_mfma_f32_16x16x32_bf16 v[102:105], v[166:169], v[200:203], v[102:105]
	v_mfma_f32_16x16x32_bf16 v[98:101], v[174:177], v[200:203], v[98:101]
	v_mfma_f32_16x16x32_bf16 v[86:89], v[166:169], v[208:211], v[86:89]
	v_mfma_f32_16x16x32_bf16 v[82:85], v[174:177], v[208:211], v[82:85]
	s_setprio 0
	s_barrier
	s_add_i32 s20, s60, s22
	s_mov_b32 m0, s20
	ds_read_b128 v[178:181], v165 offset:16384
	ds_read_b128 v[182:185], v165 offset:17408
	ds_read_b128 v[186:189], v165 offset:18432
	ds_read_b128 v[190:193], v165 offset:19456
	ds_read_b128 v[196:199], v165 offset:20480
	ds_read_b128 v[200:203], v165 offset:21504
	ds_read_b128 v[204:207], v165 offset:22528
	ds_read_b128 v[208:211], v165 offset:23552
	global_load_lds_dwordx4 v0, s[42:43]
	s_add_i32 m0, s20, 0x2000
	s_add_u32 s20, s42, 0x80000
	s_addc_u32 s21, s43, 0
	s_add_i32 s60, s66, s22
	global_load_lds_dwordx4 v150, s[42:43]
	s_mov_b32 m0, s60
	s_nop 0
	global_load_lds_dwordx4 v0, s[20:21]
	s_add_i32 m0, s60, 0x2000
	s_nop 0
	global_load_lds_dwordx4 v150, s[20:21]
	s_mov_b32 m0, s23
	s_nop 0
	global_load_lds_dwordx4 v146, s[44:45]
	s_mov_b32 m0, s24
	s_nop 0
	global_load_lds_dwordx4 v148, s[44:45]
	s_waitcnt vmcnt(8)
	s_waitcnt lgkmcnt(0)
	s_barrier
	s_setprio 1
	s_waitcnt lgkmcnt(0)
	v_mfma_f32_16x16x32_bf16 v[78:81], v[34:37], v[178:181], v[78:81]
	v_mfma_f32_16x16x32_bf16 v[74:77], v[50:53], v[178:181], v[74:77]
	v_mfma_f32_16x16x32_bf16 v[62:65], v[34:37], v[186:189], v[62:65]
	v_mfma_f32_16x16x32_bf16 v[58:61], v[50:53], v[186:189], v[58:61]
	v_mfma_f32_16x16x32_bf16 v[30:33], v[34:37], v[196:199], v[30:33]
	v_mfma_f32_16x16x32_bf16 v[26:29], v[50:53], v[196:199], v[26:29]
	v_mfma_f32_16x16x32_bf16 v[14:17], v[34:37], v[204:207], v[14:17]
	v_mfma_f32_16x16x32_bf16 v[10:13], v[50:53], v[204:207], v[10:13]
	v_mfma_f32_16x16x32_bf16 v[78:81], v[38:41], v[182:185], v[78:81]
	v_mfma_f32_16x16x32_bf16 v[74:77], v[54:57], v[182:185], v[74:77]
	v_mfma_f32_16x16x32_bf16 v[62:65], v[38:41], v[190:193], v[62:65]
	v_mfma_f32_16x16x32_bf16 v[58:61], v[54:57], v[190:193], v[58:61]
	v_mfma_f32_16x16x32_bf16 v[30:33], v[38:41], v[200:203], v[30:33]
	v_mfma_f32_16x16x32_bf16 v[26:29], v[54:57], v[200:203], v[26:29]
	v_mfma_f32_16x16x32_bf16 v[14:17], v[38:41], v[208:211], v[14:17]
	v_mfma_f32_16x16x32_bf16 v[10:13], v[54:57], v[208:211], v[10:13]
	s_setprio 0
	s_setprio 1
	v_mfma_f32_16x16x32_bf16 v[46:49], v[160:163], v[186:189], v[46:49]
	v_mfma_f32_16x16x32_bf16 v[42:45], v[170:173], v[186:189], v[42:45]
	v_mfma_f32_16x16x32_bf16 v[22:25], v[160:163], v[196:199], v[22:25]
	v_mfma_f32_16x16x32_bf16 v[18:21], v[170:173], v[196:199], v[18:21]
	v_mfma_f32_16x16x32_bf16 v[6:9], v[160:163], v[204:207], v[6:9]
	v_mfma_f32_16x16x32_bf16 v[2:5], v[170:173], v[204:207], v[2:5]
	v_mfma_f32_16x16x32_bf16 v[34:37], v[160:163], v[178:181], v[70:73]
	v_mfma_f32_16x16x32_bf16 v[38:41], v[170:173], v[178:181], v[66:69]
	v_mfma_f32_16x16x32_bf16 v[46:49], v[166:169], v[190:193], v[46:49]
	v_mfma_f32_16x16x32_bf16 v[42:45], v[174:177], v[190:193], v[42:45]
	v_mfma_f32_16x16x32_bf16 v[22:25], v[166:169], v[200:203], v[22:25]
	v_mfma_f32_16x16x32_bf16 v[18:21], v[174:177], v[200:203], v[18:21]
	v_mfma_f32_16x16x32_bf16 v[6:9], v[166:169], v[208:211], v[6:9]
	v_mfma_f32_16x16x32_bf16 v[2:5], v[174:177], v[208:211], v[2:5]
	v_mfma_f32_16x16x32_bf16 v[34:37], v[166:169], v[182:185], v[34:37]
	v_mfma_f32_16x16x32_bf16 v[38:41], v[174:177], v[182:185], v[38:41]
	s_setprio 0
	s_barrier
; #define PG8_STAGE(bufoff, gbase, voff) do { _Pragma("unroll") for (int _i = 0; _i < 2; ++_i) \
;         __builtin_amdgcn_global_load_lds((const unsigned*)((const char*)(gbase) + (voff)[_i]), (PG8_LAS unsigned*)(lds + (bufoff) + ldsw + _i * 8192), 16, 0, 0); } while (0)
; #define PG8_LDA(dst, b, h) do { _Pragma("unroll") for (int m = 0; m < 4; ++m) _Pragma("unroll") for (int k = 0; k < 2; ++k) dst[m][k] = *(const PG8_LAS bf16x8*)(lds + PG8_SA(b, h) + aoff + m * 2048 + k * 1024); } while (0)
; #define PG8_LDB(dst, b, h) do { _Pragma("unroll") for (int n = 0; n < 2; ++n) _Pragma("unroll") for (int k = 0; k < 2; ++k) dst[n][k] = *(const PG8_LAS bf16x8*)(lds + PG8_SB(b, h) + boff + n * 2048 + k * 1024); } while (0)
; #define PG8_MMA(ai, bj, At, Bt) do { __builtin_amdgcn_s_setprio(1); _Pragma("unroll") for (int m = 0; m < 4; ++m) _Pragma("unroll") for (int n = 0; n < 2; ++n) _Pragma("unroll") for (int k = 0; k < 2; ++k) \
;         acc[ai][bj][m][n] = __builtin_amdgcn_mfma_f32_16x16x32_bf16(Bt[n][k], At[m][k], acc[ai][bj][m][n], 0, 0, 0); __builtin_amdgcn_s_setprio(0); } while (0)
; #define PG8_WAIT_V(n) asm volatile("s_waitcnt vmcnt(" #n ")" ::: "memory")
; #define PG8_WAIT_L(n) asm volatile("s_waitcnt lgkmcnt(" #n ")" ::: "memory")
; #define PG8_BAR __builtin_amdgcn_s_barrier()
; #define PG8_SCHED __builtin_amdgcn_sched_barrier(0)
; template <class Epi, class Sched, bool ALIGN_EPI = false, bool SP2 = false>
; __device__ __forceinline__ void gemm_phase(PG8_LAS unsigned char* lds, const Sched& S, const Epi& E, int wave_id) {
;     ...
;             PG8_LDB(B0, 1, 0); PG8_LDB(B1, 1, 1); PG8_SCHED; PG8_LDA(At, 1, 0); PG8_STAGE(PG8_SA(0, 1), a2 + hstep, voffA);
;             PG8_WAIT_V(8); PG8_WAIT_L(0); PG8_BAR; PG8_MMA(0, 0, At, B0); PG8_MMA(0, 1, At, B1); PG8_BAR; PG8_SCHED;
;             PG8_LDA(At, 1, 1); PG8_STAGE(PG8_SB(1, 0), b3, voffB); PG8_STAGE(PG8_SB(1, 1), b3 + hstep, voffB); PG8_STAGE(PG8_SA(1, 0), a3, voffA);
;             PG8_WAIT_V(8); PG8_WAIT_L(0); PG8_BAR; PG8_MMA(1, 0, At, B0); PG8_MMA(1, 1, At, B1); PG8_BAR; PG8_SCHED;
	s_add_i32 s60, 0, 0x18000
	s_add_i32 s66, 0, 0x1c000
	v_add_u32_e32 v70, s60, v164
	v_add_u32_e32 v174, s66, v164
	ds_read_b128 v[50:53], v70
	ds_read_b128 v[54:57], v70 offset:1024
	ds_read_b128 v[66:69], v70 offset:2048
	ds_read_b128 v[70:73], v70 offset:3072
	ds_read_b128 v[160:163], v174
	ds_read_b128 v[166:169], v174 offset:1024
	ds_read_b128 v[170:173], v174 offset:2048
	ds_read_b128 v[174:177], v174 offset:3072
	s_add_u32 s20, s44, 0x80000
	s_addc_u32 s21, s45, 0
	s_mov_b32 m0, s25
	ds_read_b128 v[178:181], v165 offset:32768
	ds_read_b128 v[182:185], v165 offset:33792
	ds_read_b128 v[186:189], v165 offset:34816
	ds_read_b128 v[190:193], v165 offset:35840
	ds_read_b128 v[196:199], v165 offset:36864
	ds_read_b128 v[200:203], v165 offset:37888
	ds_read_b128 v[204:207], v165 offset:38912
	ds_read_b128 v[208:211], v165 offset:39936
	global_load_lds_dwordx4 v146, s[20:21]
	s_mov_b32 m0, s33
	s_nop 0
	global_load_lds_dwordx4 v148, s[20:21]
	s_waitcnt vmcnt(8)
	s_waitcnt lgkmcnt(0)
	s_barrier
	s_setprio 1
	s_waitcnt lgkmcnt(0)
	v_mfma_f32_16x16x32_bf16 v[142:145], v[50:53], v[178:181], v[142:145]
	v_mfma_f32_16x16x32_bf16 v[138:141], v[66:69], v[178:181], v[138:141]
	v_mfma_f32_16x16x32_bf16 v[126:129], v[50:53], v[186:189], v[126:129]
	v_mfma_f32_16x16x32_bf16 v[122:125], v[66:69], v[186:189], v[122:125]
	v_mfma_f32_16x16x32_bf16 v[110:113], v[50:53], v[196:199], v[110:113]
	v_mfma_f32_16x16x32_bf16 v[106:109], v[66:69], v[196:199], v[106:109]
	v_mfma_f32_16x16x32_bf16 v[94:97], v[50:53], v[204:207], v[94:97]
	v_mfma_f32_16x16x32_bf16 v[90:93], v[66:69], v[204:207], v[90:93]
	v_mfma_f32_16x16x32_bf16 v[142:145], v[54:57], v[182:185], v[142:145]
	v_mfma_f32_16x16x32_bf16 v[138:141], v[70:73], v[182:185], v[138:141]
	v_mfma_f32_16x16x32_bf16 v[126:129], v[54:57], v[190:193], v[126:129]
	v_mfma_f32_16x16x32_bf16 v[122:125], v[70:73], v[190:193], v[122:125]
	v_mfma_f32_16x16x32_bf16 v[110:113], v[54:57], v[200:203], v[110:113]
	v_mfma_f32_16x16x32_bf16 v[106:109], v[70:73], v[200:203], v[106:109]
	v_mfma_f32_16x16x32_bf16 v[94:97], v[54:57], v[208:211], v[94:97]
	v_mfma_f32_16x16x32_bf16 v[90:93], v[70:73], v[208:211], v[90:93]
	s_setprio 0
	s_setprio 1
	v_mfma_f32_16x16x32_bf16 v[134:137], v[160:163], v[178:181], v[134:137]
	v_mfma_f32_16x16x32_bf16 v[130:133], v[170:173], v[178:181], v[130:133]
	v_mfma_f32_16x16x32_bf16 v[118:121], v[160:163], v[186:189], v[118:121]
	v_mfma_f32_16x16x32_bf16 v[114:117], v[170:173], v[186:189], v[114:117]
	v_mfma_f32_16x16x32_bf16 v[102:105], v[160:163], v[196:199], v[102:105]
	v_mfma_f32_16x16x32_bf16 v[98:101], v[170:173], v[196:199], v[98:101]
	v_mfma_f32_16x16x32_bf16 v[86:89], v[160:163], v[204:207], v[86:89]
	v_mfma_f32_16x16x32_bf16 v[82:85], v[170:173], v[204:207], v[82:85]
	v_mfma_f32_16x16x32_bf16 v[134:137], v[166:169], v[182:185], v[134:137]
	v_mfma_f32_16x16x32_bf16 v[130:133], v[174:177], v[182:185], v[130:133]
	v_mfma_f32_16x16x32_bf16 v[118:121], v[166:169], v[190:193], v[118:121]
	v_mfma_f32_16x16x32_bf16 v[114:117], v[174:177], v[190:193], v[114:117]
	v_mfma_f32_16x16x32_bf16 v[102:105], v[166:169], v[200:203], v[102:105]
	v_mfma_f32_16x16x32_bf16 v[98:101], v[174:177], v[200:203], v[98:101]
	v_mfma_f32_16x16x32_bf16 v[86:89], v[166:169], v[208:211], v[86:89]
	v_mfma_f32_16x16x32_bf16 v[82:85], v[174:177], v[208:211], v[82:85]
	s_setprio 0
	s_barrier
	s_add_i32 s20, s60, s22
	s_sub_i32 m0, s20, 0x80
	ds_read_b128 v[178:181], v165 offset:49152
	ds_read_b128 v[182:185], v165 offset:50176
	ds_read_b128 v[186:189], v165 offset:51200
	ds_read_b128 v[190:193], v165 offset:52224
	ds_read_b128 v[196:199], v165 offset:53248
	ds_read_b128 v[200:203], v165 offset:54272
	ds_read_b128 v[204:207], v165 offset:55296
	ds_read_b128 v[208:211], v165 offset:56320
	global_load_lds_dwordx4 v0, s[42:43] offset:128
	s_add_i32 m0, s20, 0x1f80
	s_add_u32 s20, s42, 0x80080
	s_addc_u32 s21, s43, 0
	s_add_i32 s98, s66, s22
	global_load_lds_dwordx4 v150, s[42:43] offset:128
	s_mov_b32 m0, s98
	s_nop 0
	global_load_lds_dwordx4 v0, s[20:21]
	s_add_i32 m0, s98, 0x2000
	s_nop 0
	global_load_lds_dwordx4 v150, s[20:21]
	s_sub_i32 m0, s48, 0x80
	s_nop 0
	global_load_lds_dwordx4 v146, s[44:45] offset:128
	s_sub_i32 m0, s49, 0x80
	s_nop 0
	global_load_lds_dwordx4 v148, s[44:45] offset:128
	s_waitcnt vmcnt(8)
	s_waitcnt lgkmcnt(0)
	s_barrier
	s_setprio 1
	s_waitcnt lgkmcnt(0)
	v_mfma_f32_16x16x32_bf16 v[78:81], v[50:53], v[178:181], v[78:81]
	v_mfma_f32_16x16x32_bf16 v[74:77], v[66:69], v[178:181], v[74:77]
	v_mfma_f32_16x16x32_bf16 v[62:65], v[50:53], v[186:189], v[62:65]
	v_mfma_f32_16x16x32_bf16 v[58:61], v[66:69], v[186:189], v[58:61]
	v_mfma_f32_16x16x32_bf16 v[30:33], v[50:53], v[196:199], v[30:33]
	v_mfma_f32_16x16x32_bf16 v[26:29], v[66:69], v[196:199], v[26:29]
	v_mfma_f32_16x16x32_bf16 v[14:17], v[50:53], v[204:207], v[14:17]
	v_mfma_f32_16x16x32_bf16 v[10:13], v[66:69], v[204:207], v[10:13]
	v_mfma_f32_16x16x32_bf16 v[78:81], v[54:57], v[182:185], v[78:81]
	v_mfma_f32_16x16x32_bf16 v[74:77], v[70:73], v[182:185], v[74:77]
	v_mfma_f32_16x16x32_bf16 v[62:65], v[54:57], v[190:193], v[62:65]
	v_mfma_f32_16x16x32_bf16 v[58:61], v[70:73], v[190:193], v[58:61]
	v_mfma_f32_16x16x32_bf16 v[30:33], v[54:57], v[200:203], v[30:33]
	v_mfma_f32_16x16x32_bf16 v[26:29], v[70:73], v[200:203], v[26:29]
	v_mfma_f32_16x16x32_bf16 v[14:17], v[54:57], v[208:211], v[14:17]
	v_mfma_f32_16x16x32_bf16 v[10:13], v[70:73], v[208:211], v[10:13]
	s_setprio 0
	s_setprio 1
	v_mfma_f32_16x16x32_bf16 v[34:37], v[160:163], v[178:181], v[34:37]
	v_mfma_f32_16x16x32_bf16 v[70:73], v[166:169], v[182:185], v[34:37]
	v_mfma_f32_16x16x32_bf16 v[34:37], v[170:173], v[178:181], v[38:41]
	v_mfma_f32_16x16x32_bf16 v[66:69], v[174:177], v[182:185], v[34:37]
	v_mfma_f32_16x16x32_bf16 v[34:37], v[160:163], v[186:189], v[46:49]
	v_mfma_f32_16x16x32_bf16 v[46:49], v[166:169], v[190:193], v[34:37]
	v_mfma_f32_16x16x32_bf16 v[34:37], v[170:173], v[186:189], v[42:45]
	v_mfma_f32_16x16x32_bf16 v[22:25], v[160:163], v[196:199], v[22:25]
	v_mfma_f32_16x16x32_bf16 v[18:21], v[170:173], v[196:199], v[18:21]
	v_mfma_f32_16x16x32_bf16 v[6:9], v[160:163], v[204:207], v[6:9]
	v_mfma_f32_16x16x32_bf16 v[2:5], v[170:173], v[204:207], v[2:5]
	v_mfma_f32_16x16x32_bf16 v[42:45], v[174:177], v[190:193], v[34:37]
	v_mfma_f32_16x16x32_bf16 v[22:25], v[166:169], v[200:203], v[22:25]
	v_mfma_f32_16x16x32_bf16 v[18:21], v[174:177], v[200:203], v[18:21]
	v_mfma_f32_16x16x32_bf16 v[6:9], v[166:169], v[208:211], v[6:9]
	v_mfma_f32_16x16x32_bf16 v[2:5], v[174:177], v[208:211], v[2:5]
	s_setprio 0
	s_barrier
	s_add_i32 s19, s19, 2
	s_add_u32 s38, s38, 0x100
	s_addc_u32 s39, s39, 0
	s_add_u32 s16, s16, 0x100
	s_addc_u32 s17, s17, 0
	s_cmp_gt_u32 s19, 29
	s_cbranch_scc0 .LBB0_89
	s_and_b64 vcc, exec, s[12:13]
	s_cbranch_vccz .LBB0_92
	s_barrier

; #define PG8_STAGE(bufoff, gbase, voff) do { _Pragma("unroll") for (int _i = 0; _i < 2; ++_i) \
;         __builtin_amdgcn_global_load_lds((const unsigned*)((const char*)(gbase) + (voff)[_i]), (PG8_LAS unsigned*)(lds + (bufoff) + ldsw + _i * 8192), 16, 0, 0); } while (0)
; #define PG8_LDA(dst, b, h) do { _Pragma("unroll") for (int m = 0; m < 4; ++m) _Pragma("unroll") for (int k = 0; k < 2; ++k) dst[m][k] = *(const PG8_LAS bf16x8*)(lds + PG8_SA(b, h) + aoff + m * 2048 + k * 1024); } while (0)
; #define PG8_LDB(dst, b, h) do { _Pragma("unroll") for (int n = 0; n < 2; ++n) _Pragma("unroll") for (int k = 0; k < 2; ++k) dst[n][k] = *(const PG8_LAS bf16x8*)(lds + PG8_SB(b, h) + boff + n * 2048 + k * 1024); } while (0)
; #define PG8_MMA(ai, bj, At, Bt) do { __builtin_amdgcn_s_setprio(1); _Pragma("unroll") for (int m = 0; m < 4; ++m) _Pragma("unroll") for (int n = 0; n < 2; ++n) _Pragma("unroll") for (int k = 0; k < 2; ++k) \
;         acc[ai][bj][m][n] = __builtin_amdgcn_mfma_f32_16x16x32_bf16(Bt[n][k], At[m][k], acc[ai][bj][m][n], 0, 0, 0); __builtin_amdgcn_s_setprio(0); } while (0)
; #define PG8_WAIT_V(n) asm volatile("s_waitcnt vmcnt(" #n ")" ::: "memory")
; #define PG8_WAIT_L(n) asm volatile("s_waitcnt lgkmcnt(" #n ")" ::: "memory")
; #define PG8_BAR __builtin_amdgcn_s_barrier()
; #define PG8_SCHED __builtin_amdgcn_sched_barrier(0)
; template <class Epi, class Sched, bool ALIGN_EPI = false, bool SP2 = false>
; __device__ __forceinline__ void gemm_phase(PG8_LAS unsigned char* lds, const Sched& S, const Epi& E, int wave_id) {
;     ...
;             PG8_LDB(B0, 0, 0); PG8_LDB(B1, 0, 1); PG8_SCHED; PG8_LDA(At, 0, 0); PG8_STAGE(PG8_SA(1, 1), a1 + hstep, voffA);
;             PG8_WAIT_V(8); PG8_WAIT_L(0); PG8_BAR; PG8_MMA(0, 0, At, B0); PG8_MMA(0, 1, At, B1); PG8_BAR; PG8_SCHED;
;             PG8_LDA(At, 0, 1); PG8_STAGE(PG8_SB(0, 0), b2, voffB); PG8_STAGE(PG8_SB(0, 1), b2 + hstep, voffB); PG8_STAGE(PG8_SA(0, 0), a2, voffA);
;             PG8_WAIT_V(8); PG8_WAIT_L(0); PG8_BAR; PG8_MMA(1, 0, At, B0); PG8_MMA(1, 1, At, B1); PG8_BAR; PG8_SCHED;
.LBB0_839:
	s_add_i32 s66, s40, 2
	s_add_u32 s41, s38, 0xfff80080
	s_addc_u32 s44, s39, -1
	s_add_i32 s67, 0, 0x10000
	s_cmp_eq_u32 s30, s40
	s_cselect_b32 s45, s37, s44
	s_cselect_b32 s44, s36, s41
	s_cselect_b32 s41, s43, s47
	s_cselect_b32 s40, s42, s46
	s_add_i32 s79, 0, 0x14000
	v_add_u32_e32 v142, s67, v194
	v_add_u32_e32 v158, s79, v194
	ds_read_b128 v[130:133], v142
	ds_read_b128 v[134:137], v142 offset:1024
	ds_read_b128 v[138:141], v142 offset:2048
	ds_read_b128 v[142:145], v142 offset:3072
	ds_read_b128 v[146:149], v158
	ds_read_b128 v[150:153], v158 offset:1024
	ds_read_b128 v[154:157], v158 offset:2048
	ds_read_b128 v[158:161], v158 offset:3072
	s_add_i32 m0, s23, 0xc000
	ds_read_b128 v[162:165], v244
	ds_read_b128 v[166:169], v244 offset:1024
	ds_read_b128 v[170:173], v244 offset:2048
	ds_read_b128 v[174:177], v244 offset:3072
	ds_read_b128 v[178:181], v244 offset:4096
	ds_read_b128 v[182:185], v244 offset:5120
	ds_read_b128 v[186:189], v244 offset:6144
	ds_read_b128 v[190:193], v244 offset:7168
	global_load_lds_dwordx4 v206, s[38:39]
	s_add_i32 m0, s23, 0xe000
	s_nop 0
	global_load_lds_dwordx4 v208, s[38:39]
	s_waitcnt vmcnt(8)
	s_waitcnt lgkmcnt(0)
	s_barrier
	s_setprio 1
	s_waitcnt lgkmcnt(0)
	v_mfma_f32_16x16x32_bf16 v[126:129], v[130:133], v[162:165], v[126:129]
	v_mfma_f32_16x16x32_bf16 v[122:125], v[138:141], v[162:165], v[122:125]
	v_mfma_f32_16x16x32_bf16 v[110:113], v[130:133], v[170:173], v[110:113]
	v_mfma_f32_16x16x32_bf16 v[106:109], v[138:141], v[170:173], v[106:109]
	v_mfma_f32_16x16x32_bf16 v[94:97], v[130:133], v[178:181], v[94:97]
	v_mfma_f32_16x16x32_bf16 v[90:93], v[138:141], v[178:181], v[90:93]
	v_mfma_f32_16x16x32_bf16 v[78:81], v[130:133], v[186:189], v[78:81]
	v_mfma_f32_16x16x32_bf16 v[74:77], v[138:141], v[186:189], v[74:77]
	v_mfma_f32_16x16x32_bf16 v[126:129], v[134:137], v[166:169], v[126:129]
	v_mfma_f32_16x16x32_bf16 v[122:125], v[142:145], v[166:169], v[122:125]
	v_mfma_f32_16x16x32_bf16 v[110:113], v[134:137], v[174:177], v[110:113]
	v_mfma_f32_16x16x32_bf16 v[106:109], v[142:145], v[174:177], v[106:109]
	v_mfma_f32_16x16x32_bf16 v[94:97], v[134:137], v[182:185], v[94:97]
	v_mfma_f32_16x16x32_bf16 v[90:93], v[142:145], v[182:185], v[90:93]
	v_mfma_f32_16x16x32_bf16 v[78:81], v[134:137], v[190:193], v[78:81]
	v_mfma_f32_16x16x32_bf16 v[74:77], v[142:145], v[190:193], v[74:77]
	s_setprio 0
	s_setprio 1
	v_mfma_f32_16x16x32_bf16 v[118:121], v[146:149], v[162:165], v[118:121]
	v_mfma_f32_16x16x32_bf16 v[114:117], v[154:157], v[162:165], v[114:117]
	v_mfma_f32_16x16x32_bf16 v[102:105], v[146:149], v[170:173], v[102:105]
	v_mfma_f32_16x16x32_bf16 v[98:101], v[154:157], v[170:173], v[98:101]
	v_mfma_f32_16x16x32_bf16 v[86:89], v[146:149], v[178:181], v[86:89]
	v_mfma_f32_16x16x32_bf16 v[82:85], v[154:157], v[178:181], v[82:85]
	v_mfma_f32_16x16x32_bf16 v[70:73], v[146:149], v[186:189], v[70:73]
	v_mfma_f32_16x16x32_bf16 v[66:69], v[154:157], v[186:189], v[66:69]
	v_mfma_f32_16x16x32_bf16 v[118:121], v[150:153], v[166:169], v[118:121]
	v_mfma_f32_16x16x32_bf16 v[114:117], v[158:161], v[166:169], v[114:117]
	v_mfma_f32_16x16x32_bf16 v[102:105], v[150:153], v[174:177], v[102:105]
	v_mfma_f32_16x16x32_bf16 v[98:101], v[158:161], v[174:177], v[98:101]
	v_mfma_f32_16x16x32_bf16 v[86:89], v[150:153], v[182:185], v[86:89]
	v_mfma_f32_16x16x32_bf16 v[82:85], v[158:161], v[182:185], v[82:85]
	v_mfma_f32_16x16x32_bf16 v[70:73], v[150:153], v[190:193], v[70:73]
	v_mfma_f32_16x16x32_bf16 v[66:69], v[158:161], v[190:193], v[66:69]
	s_setprio 0
	s_barrier
	s_add_i32 s67, s67, s22
	s_mov_b32 m0, s67
	ds_read_b128 v[162:165], v244 offset:16384
	ds_read_b128 v[166:169], v244 offset:17408
	ds_read_b128 v[170:173], v244 offset:18432
	ds_read_b128 v[174:177], v244 offset:19456
	ds_read_b128 v[178:181], v244 offset:20480
	ds_read_b128 v[182:185], v244 offset:21504
	ds_read_b128 v[186:189], v244 offset:22528
	ds_read_b128 v[190:193], v244 offset:23552
	global_load_lds_dwordx4 v0, s[40:41]
	s_add_i32 m0, s67, 0x2000
	s_add_u32 vcc_lo, s40, 0x80000
	s_addc_u32 vcc_hi, s41, 0
	s_add_i32 s67, s79, s22
	global_load_lds_dwordx4 v200, s[40:41]
	s_mov_b32 m0, s67
	s_nop 0
	global_load_lds_dwordx4 v0, vcc
	s_add_i32 m0, s67, 0x2000
	s_nop 0
	global_load_lds_dwordx4 v200, vcc
	s_mov_b32 m0, s23
	s_nop 0
	global_load_lds_dwordx4 v196, s[44:45]
	s_mov_b32 m0, s24
	s_nop 0
	global_load_lds_dwordx4 v198, s[44:45]
	s_waitcnt vmcnt(8)
	s_waitcnt lgkmcnt(0)
	s_barrier
	s_setprio 1
	s_waitcnt lgkmcnt(0)
	v_mfma_f32_16x16x32_bf16 v[62:65], v[130:133], v[162:165], v[62:65]
	v_mfma_f32_16x16x32_bf16 v[58:61], v[138:141], v[162:165], v[58:61]
	v_mfma_f32_16x16x32_bf16 v[46:49], v[130:133], v[170:173], v[46:49]
	v_mfma_f32_16x16x32_bf16 v[42:45], v[138:141], v[170:173], v[42:45]
	v_mfma_f32_16x16x32_bf16 v[30:33], v[130:133], v[178:181], v[30:33]
	v_mfma_f32_16x16x32_bf16 v[26:29], v[138:141], v[178:181], v[26:29]
	v_mfma_f32_16x16x32_bf16 v[14:17], v[130:133], v[186:189], v[14:17]
	v_mfma_f32_16x16x32_bf16 v[10:13], v[138:141], v[186:189], v[10:13]
	v_mfma_f32_16x16x32_bf16 v[62:65], v[134:137], v[166:169], v[62:65]
	v_mfma_f32_16x16x32_bf16 v[58:61], v[142:145], v[166:169], v[58:61]
	v_mfma_f32_16x16x32_bf16 v[46:49], v[134:137], v[174:177], v[46:49]
	v_mfma_f32_16x16x32_bf16 v[42:45], v[142:145], v[174:177], v[42:45]
	v_mfma_f32_16x16x32_bf16 v[30:33], v[134:137], v[182:185], v[30:33]
	v_mfma_f32_16x16x32_bf16 v[26:29], v[142:145], v[182:185], v[26:29]
	v_mfma_f32_16x16x32_bf16 v[14:17], v[134:137], v[190:193], v[14:17]
	v_mfma_f32_16x16x32_bf16 v[10:13], v[142:145], v[190:193], v[10:13]
	s_setprio 0
	s_setprio 1
	v_mfma_f32_16x16x32_bf16 v[54:57], v[146:149], v[162:165], v[54:57]
	v_mfma_f32_16x16x32_bf16 v[50:53], v[154:157], v[162:165], v[50:53]
	v_mfma_f32_16x16x32_bf16 v[38:41], v[146:149], v[170:173], v[38:41]
	v_mfma_f32_16x16x32_bf16 v[34:37], v[154:157], v[170:173], v[34:37]
	v_mfma_f32_16x16x32_bf16 v[22:25], v[146:149], v[178:181], v[22:25]
	v_mfma_f32_16x16x32_bf16 v[18:21], v[154:157], v[178:181], v[18:21]
	v_mfma_f32_16x16x32_bf16 v[6:9], v[146:149], v[186:189], v[6:9]
	v_mfma_f32_16x16x32_bf16 v[2:5], v[154:157], v[186:189], v[2:5]
	v_mfma_f32_16x16x32_bf16 v[54:57], v[150:153], v[166:169], v[54:57]
	v_mfma_f32_16x16x32_bf16 v[50:53], v[158:161], v[166:169], v[50:53]
	v_mfma_f32_16x16x32_bf16 v[38:41], v[150:153], v[174:177], v[38:41]
	v_mfma_f32_16x16x32_bf16 v[34:37], v[158:161], v[174:177], v[34:37]
	v_mfma_f32_16x16x32_bf16 v[22:25], v[150:153], v[182:185], v[22:25]
	v_mfma_f32_16x16x32_bf16 v[18:21], v[158:161], v[182:185], v[18:21]
	v_mfma_f32_16x16x32_bf16 v[6:9], v[150:153], v[190:193], v[6:9]
	v_mfma_f32_16x16x32_bf16 v[2:5], v[158:161], v[190:193], v[2:5]
	s_setprio 0
	s_barrier
; #define PG8_STAGE(bufoff, gbase, voff) do { _Pragma("unroll") for (int _i = 0; _i < 2; ++_i) \
;         __builtin_amdgcn_global_load_lds((const unsigned*)((const char*)(gbase) + (voff)[_i]), (PG8_LAS unsigned*)(lds + (bufoff) + ldsw + _i * 8192), 16, 0, 0); } while (0)
; #define PG8_LDA(dst, b, h) do { _Pragma("unroll") for (int m = 0; m < 4; ++m) _Pragma("unroll") for (int k = 0; k < 2; ++k) dst[m][k] = *(const PG8_LAS bf16x8*)(lds + PG8_SA(b, h) + aoff + m * 2048 + k * 1024); } while (0)
; #define PG8_LDB(dst, b, h) do { _Pragma("unroll") for (int n = 0; n < 2; ++n) _Pragma("unroll") for (int k = 0; k < 2; ++k) dst[n][k] = *(const PG8_LAS bf16x8*)(lds + PG8_SB(b, h) + boff + n * 2048 + k * 1024); } while (0)
; #define PG8_MMA(ai, bj, At, Bt) do { __builtin_amdgcn_s_setprio(1); _Pragma("unroll") for (int m = 0; m < 4; ++m) _Pragma("unroll") for (int n = 0; n < 2; ++n) _Pragma("unroll") for (int k = 0; k < 2; ++k) \
;         acc[ai][bj][m][n] = __builtin_amdgcn_mfma_f32_16x16x32_bf16(Bt[n][k], At[m][k], acc[ai][bj][m][n], 0, 0, 0); __builtin_amdgcn_s_setprio(0); } while (0)
; #define PG8_WAIT_V(n) asm volatile("s_waitcnt vmcnt(" #n ")" ::: "memory")
; #define PG8_WAIT_L(n) asm volatile("s_waitcnt lgkmcnt(" #n ")" ::: "memory")
; #define PG8_BAR __builtin_amdgcn_s_barrier()
; #define PG8_SCHED __builtin_amdgcn_sched_barrier(0)
; template <class Epi, class Sched, bool ALIGN_EPI = false, bool SP2 = false>
; __device__ __forceinline__ void gemm_phase(PG8_LAS unsigned char* lds, const Sched& S, const Epi& E, int wave_id) {
;     ...
;             PG8_LDB(B0, 1, 0); PG8_LDB(B1, 1, 1); PG8_SCHED; PG8_LDA(At, 1, 0); PG8_STAGE(PG8_SA(0, 1), a2 + hstep, voffA);
;             PG8_WAIT_V(8); PG8_WAIT_L(0); PG8_BAR; PG8_MMA(0, 0, At, B0); PG8_MMA(0, 1, At, B1); PG8_BAR; PG8_SCHED;
;             PG8_LDA(At, 1, 1); PG8_STAGE(PG8_SB(1, 0), b3, voffB); PG8_STAGE(PG8_SB(1, 1), b3 + hstep, voffB); PG8_STAGE(PG8_SA(1, 0), a3, voffA);
;             PG8_WAIT_V(8); PG8_WAIT_L(0); PG8_BAR; PG8_MMA(1, 0, At, B0); PG8_MMA(1, 1, At, B1); PG8_BAR; PG8_SCHED;
	s_add_i32 s67, 0, 0x18000
	s_add_i32 s79, 0, 0x1c000
	v_add_u32_e32 v142, s67, v194
	v_add_u32_e32 v158, s79, v194
	ds_read_b128 v[130:133], v142
	ds_read_b128 v[134:137], v142 offset:1024
	ds_read_b128 v[138:141], v142 offset:2048
	ds_read_b128 v[142:145], v142 offset:3072
	ds_read_b128 v[146:149], v158
	ds_read_b128 v[150:153], v158 offset:1024
	ds_read_b128 v[154:157], v158 offset:2048
	ds_read_b128 v[158:161], v158 offset:3072
	s_add_u32 s98, s44, 0x80000
	s_addc_u32 s99, s45, 0
	s_mov_b32 m0, s25
	ds_read_b128 v[162:165], v244 offset:32768
	ds_read_b128 v[166:169], v244 offset:33792
	ds_read_b128 v[170:173], v244 offset:34816
	ds_read_b128 v[174:177], v244 offset:35840
	ds_read_b128 v[178:181], v244 offset:36864
	ds_read_b128 v[182:185], v244 offset:37888
	ds_read_b128 v[186:189], v244 offset:38912
	ds_read_b128 v[190:193], v244 offset:39936
	global_load_lds_dwordx4 v196, s[98:99]
	s_mov_b32 m0, s33
	s_nop 0
	global_load_lds_dwordx4 v198, s[98:99]
	s_waitcnt vmcnt(8)
	s_waitcnt lgkmcnt(0)
	s_barrier
	s_setprio 1
	s_waitcnt lgkmcnt(0)
	v_mfma_f32_16x16x32_bf16 v[126:129], v[130:133], v[162:165], v[126:129]
	v_mfma_f32_16x16x32_bf16 v[122:125], v[138:141], v[162:165], v[122:125]
	v_mfma_f32_16x16x32_bf16 v[110:113], v[130:133], v[170:173], v[110:113]
	v_mfma_f32_16x16x32_bf16 v[106:109], v[138:141], v[170:173], v[106:109]
	v_mfma_f32_16x16x32_bf16 v[94:97], v[130:133], v[178:181], v[94:97]
	v_mfma_f32_16x16x32_bf16 v[90:93], v[138:141], v[178:181], v[90:93]
	v_mfma_f32_16x16x32_bf16 v[78:81], v[130:133], v[186:189], v[78:81]
	v_mfma_f32_16x16x32_bf16 v[74:77], v[138:141], v[186:189], v[74:77]
	v_mfma_f32_16x16x32_bf16 v[126:129], v[134:137], v[166:169], v[126:129]
	v_mfma_f32_16x16x32_bf16 v[122:125], v[142:145], v[166:169], v[122:125]
	v_mfma_f32_16x16x32_bf16 v[110:113], v[134:137], v[174:177], v[110:113]
	v_mfma_f32_16x16x32_bf16 v[106:109], v[142:145], v[174:177], v[106:109]
	v_mfma_f32_16x16x32_bf16 v[94:97], v[134:137], v[182:185], v[94:97]
	v_mfma_f32_16x16x32_bf16 v[90:93], v[142:145], v[182:185], v[90:93]
	v_mfma_f32_16x16x32_bf16 v[78:81], v[134:137], v[190:193], v[78:81]
	v_mfma_f32_16x16x32_bf16 v[74:77], v[142:145], v[190:193], v[74:77]
	s_setprio 0
	s_setprio 1
	v_mfma_f32_16x16x32_bf16 v[118:121], v[146:149], v[162:165], v[118:121]
	v_mfma_f32_16x16x32_bf16 v[114:117], v[154:157], v[162:165], v[114:117]
	v_mfma_f32_16x16x32_bf16 v[102:105], v[146:149], v[170:173], v[102:105]
	v_mfma_f32_16x16x32_bf16 v[98:101], v[154:157], v[170:173], v[98:101]
	v_mfma_f32_16x16x32_bf16 v[86:89], v[146:149], v[178:181], v[86:89]
	v_mfma_f32_16x16x32_bf16 v[82:85], v[154:157], v[178:181], v[82:85]
	v_mfma_f32_16x16x32_bf16 v[70:73], v[146:149], v[186:189], v[70:73]
	v_mfma_f32_16x16x32_bf16 v[66:69], v[154:157], v[186:189], v[66:69]
	v_mfma_f32_16x16x32_bf16 v[118:121], v[150:153], v[166:169], v[118:121]
	v_mfma_f32_16x16x32_bf16 v[114:117], v[158:161], v[166:169], v[114:117]
	v_mfma_f32_16x16x32_bf16 v[102:105], v[150:153], v[174:177], v[102:105]
	v_mfma_f32_16x16x32_bf16 v[98:101], v[158:161], v[174:177], v[98:101]
	v_mfma_f32_16x16x32_bf16 v[86:89], v[150:153], v[182:185], v[86:89]
	v_mfma_f32_16x16x32_bf16 v[82:85], v[158:161], v[182:185], v[82:85]
	v_mfma_f32_16x16x32_bf16 v[70:73], v[150:153], v[190:193], v[70:73]
	v_mfma_f32_16x16x32_bf16 v[66:69], v[158:161], v[190:193], v[66:69]
	s_setprio 0
	s_barrier
	s_add_i32 s100, s67, s22
	s_sub_i32 m0, s100, 0x80
	ds_read_b128 v[162:165], v244 offset:49152
	ds_read_b128 v[166:169], v244 offset:50176
	ds_read_b128 v[170:173], v244 offset:51200
	ds_read_b128 v[174:177], v244 offset:52224
	ds_read_b128 v[178:181], v244 offset:53248
	ds_read_b128 v[182:185], v244 offset:54272
	ds_read_b128 v[186:189], v244 offset:55296
	ds_read_b128 v[190:193], v244 offset:56320
	global_load_lds_dwordx4 v0, s[40:41] offset:128
	s_add_i32 m0, s100, 0x1f80
	s_add_i32 s100, s79, s22
	global_load_lds_dwordx4 v200, s[40:41] offset:128
	s_add_u32 s40, s40, 0x80080
	s_addc_u32 s41, s41, 0
	s_mov_b32 m0, s100
	s_nop 0
	global_load_lds_dwordx4 v0, s[40:41]
	s_add_i32 m0, s100, 0x2000
	s_nop 0
	global_load_lds_dwordx4 v200, s[40:41]
	s_sub_i32 m0, s17, 0x80
	s_nop 0
	global_load_lds_dwordx4 v196, s[44:45] offset:128
	s_sub_i32 m0, s4, 0x80
	s_nop 0
	global_load_lds_dwordx4 v198, s[44:45] offset:128
	s_waitcnt vmcnt(8)
	s_waitcnt lgkmcnt(0)
	s_barrier
	s_setprio 1
	s_waitcnt lgkmcnt(0)
	v_mfma_f32_16x16x32_bf16 v[62:65], v[130:133], v[162:165], v[62:65]
	v_mfma_f32_16x16x32_bf16 v[58:61], v[138:141], v[162:165], v[58:61]
	v_mfma_f32_16x16x32_bf16 v[46:49], v[130:133], v[170:173], v[46:49]
	v_mfma_f32_16x16x32_bf16 v[42:45], v[138:141], v[170:173], v[42:45]
	v_mfma_f32_16x16x32_bf16 v[30:33], v[130:133], v[178:181], v[30:33]
	v_mfma_f32_16x16x32_bf16 v[26:29], v[138:141], v[178:181], v[26:29]
	v_mfma_f32_16x16x32_bf16 v[14:17], v[130:133], v[186:189], v[14:17]
	v_mfma_f32_16x16x32_bf16 v[10:13], v[138:141], v[186:189], v[10:13]
	v_mfma_f32_16x16x32_bf16 v[62:65], v[134:137], v[166:169], v[62:65]
	v_mfma_f32_16x16x32_bf16 v[58:61], v[142:145], v[166:169], v[58:61]
	v_mfma_f32_16x16x32_bf16 v[46:49], v[134:137], v[174:177], v[46:49]
	v_mfma_f32_16x16x32_bf16 v[42:45], v[142:145], v[174:177], v[42:45]
	v_mfma_f32_16x16x32_bf16 v[30:33], v[134:137], v[182:185], v[30:33]
	v_mfma_f32_16x16x32_bf16 v[26:29], v[142:145], v[182:185], v[26:29]
	v_mfma_f32_16x16x32_bf16 v[14:17], v[134:137], v[190:193], v[14:17]
	v_mfma_f32_16x16x32_bf16 v[10:13], v[142:145], v[190:193], v[10:13]
	s_setprio 0
	s_setprio 1
	v_mfma_f32_16x16x32_bf16 v[54:57], v[146:149], v[162:165], v[54:57]
	v_mfma_f32_16x16x32_bf16 v[50:53], v[154:157], v[162:165], v[50:53]
	v_mfma_f32_16x16x32_bf16 v[38:41], v[146:149], v[170:173], v[38:41]
	v_mfma_f32_16x16x32_bf16 v[34:37], v[154:157], v[170:173], v[34:37]
	v_mfma_f32_16x16x32_bf16 v[22:25], v[146:149], v[178:181], v[22:25]
	v_mfma_f32_16x16x32_bf16 v[18:21], v[154:157], v[178:181], v[18:21]
	v_mfma_f32_16x16x32_bf16 v[6:9], v[146:149], v[186:189], v[6:9]
	v_mfma_f32_16x16x32_bf16 v[2:5], v[154:157], v[186:189], v[2:5]
	v_mfma_f32_16x16x32_bf16 v[54:57], v[150:153], v[166:169], v[54:57]
	v_mfma_f32_16x16x32_bf16 v[50:53], v[158:161], v[166:169], v[50:53]
	v_mfma_f32_16x16x32_bf16 v[38:41], v[150:153], v[174:177], v[38:41]
	v_mfma_f32_16x16x32_bf16 v[34:37], v[158:161], v[174:177], v[34:37]
	v_mfma_f32_16x16x32_bf16 v[22:25], v[150:153], v[182:185], v[22:25]
	v_mfma_f32_16x16x32_bf16 v[18:21], v[158:161], v[182:185], v[18:21]
	v_mfma_f32_16x16x32_bf16 v[6:9], v[150:153], v[190:193], v[6:9]
	v_mfma_f32_16x16x32_bf16 v[2:5], v[158:161], v[190:193], v[2:5]
	s_setprio 0
	s_barrier
	s_add_u32 s38, s38, 0x100
	s_addc_u32 s39, s39, 0
	s_add_u32 s46, s46, 0x100
	s_addc_u32 s47, s47, 0
	s_cmp_ge_i32 s66, s50
	s_mov_b32 s40, s66
	s_cbranch_scc0 .LBB0_839
	s_and_b64 vcc, exec, s[12:13]
	s_cbranch_vccz .LBB0_842
	s_barrier

; #define PG8_STAGE(bufoff, gbase, voff) do { _Pragma("unroll") for (int _i = 0; _i < 2; ++_i) \
;         __builtin_amdgcn_global_load_lds((const unsigned*)((const char*)(gbase) + (voff)[_i]), (PG8_LAS unsigned*)(lds + (bufoff) + ldsw + _i * 8192), 16, 0, 0); } while (0)
; #define PG8_LDA(dst, b, h) do { _Pragma("unroll") for (int m = 0; m < 4; ++m) _Pragma("unroll") for (int k = 0; k < 2; ++k) dst[m][k] = *(const PG8_LAS bf16x8*)(lds + PG8_SA(b, h) + aoff + m * 2048 + k * 1024); } while (0)
; #define PG8_LDB(dst, b, h) do { _Pragma("unroll") for (int n = 0; n < 2; ++n) _Pragma("unroll") for (int k = 0; k < 2; ++k) dst[n][k] = *(const PG8_LAS bf16x8*)(lds + PG8_SB(b, h) + boff + n * 2048 + k * 1024); } while (0)
; #define PG8_MMA(ai, bj, At, Bt) do { __builtin_amdgcn_s_setprio(1); _Pragma("unroll") for (int m = 0; m < 4; ++m) _Pragma("unroll") for (int n = 0; n < 2; ++n) _Pragma("unroll") for (int k = 0; k < 2; ++k) \
;         acc[ai][bj][m][n] = __builtin_amdgcn_mfma_f32_16x16x32_bf16(Bt[n][k], At[m][k], acc[ai][bj][m][n], 0, 0, 0); __builtin_amdgcn_s_setprio(0); } while (0)
; #define PG8_WAIT_V(n) asm volatile("s_waitcnt vmcnt(" #n ")" ::: "memory")
; #define PG8_WAIT_L(n) asm volatile("s_waitcnt lgkmcnt(" #n ")" ::: "memory")
; #define PG8_BAR __builtin_amdgcn_s_barrier()
; #define PG8_SCHED __builtin_amdgcn_sched_barrier(0)
; template <class Epi, class Sched, bool ALIGN_EPI = false, bool SP2 = false>
; __device__ __forceinline__ void gemm_phase(PG8_LAS unsigned char* lds, const Sched& S, const Epi& E, int wave_id) {
;     ...
;             PG8_LDB(B0, 0, 0); PG8_LDB(B1, 0, 1); PG8_SCHED; PG8_LDA(At, 0, 0); PG8_STAGE(PG8_SA(1, 1), a1 + hstep, voffA);
;             PG8_WAIT_V(8); PG8_WAIT_L(0); PG8_BAR; PG8_MMA(0, 0, At, B0); PG8_MMA(0, 1, At, B1); PG8_BAR; PG8_SCHED;
;             PG8_LDA(At, 0, 1); PG8_STAGE(PG8_SB(0, 0), b2, voffB); PG8_STAGE(PG8_SB(0, 1), b2 + hstep, voffB); PG8_STAGE(PG8_SA(0, 0), a2, voffA);
;             PG8_WAIT_V(8); PG8_WAIT_L(0); PG8_BAR; PG8_MMA(1, 0, At, B0); PG8_MMA(1, 1, At, B1); PG8_BAR; PG8_SCHED;
.LBB0_1039:
	s_add_u32 s44, s42, 0xfff80080
	s_addc_u32 s45, s43, -1
	s_add_i32 s53, 0, 0x10000
	s_cmp_eq_u32 s51, 28
	s_cselect_b32 s47, s29, s45
	s_cselect_b32 s46, s28, s44
	s_cselect_b32 s45, s37, s50
	s_cselect_b32 s44, s36, s19
	s_add_i32 s66, 0, 0x14000
	v_add_u32_e32 v142, s53, v178
	v_add_u32_e32 v158, s66, v178
	ds_read_b128 v[130:133], v142
	ds_read_b128 v[134:137], v142 offset:1024
	ds_read_b128 v[138:141], v142 offset:2048
	ds_read_b128 v[142:145], v142 offset:3072
	ds_read_b128 v[146:149], v158
	ds_read_b128 v[150:153], v158 offset:1024
	ds_read_b128 v[154:157], v158 offset:2048
	ds_read_b128 v[158:161], v158 offset:3072
	s_add_i32 m0, s11, 0xc000
	ds_read_b128 v[180:183], v179
	ds_read_b128 v[184:187], v179 offset:1024
	ds_read_b128 v[188:191], v179 offset:2048
	ds_read_b128 v[196:199], v179 offset:3072
	ds_read_b128 v[200:203], v179 offset:4096
	ds_read_b128 v[204:207], v179 offset:5120
	ds_read_b128 v[208:211], v179 offset:6144
	ds_read_b128 v[212:215], v179 offset:7168
	global_load_lds_dwordx4 v172, s[42:43]
	s_add_i32 m0, s11, 0xe000
	s_nop 0
	global_load_lds_dwordx4 v174, s[42:43]
	s_waitcnt vmcnt(8)
	s_waitcnt lgkmcnt(0)
	s_barrier
	s_setprio 1
	s_waitcnt lgkmcnt(0)
	v_mfma_f32_16x16x32_bf16 v[126:129], v[130:133], v[180:183], v[126:129]
	v_mfma_f32_16x16x32_bf16 v[122:125], v[138:141], v[180:183], v[122:125]
	v_mfma_f32_16x16x32_bf16 v[110:113], v[130:133], v[188:191], v[110:113]
	v_mfma_f32_16x16x32_bf16 v[106:109], v[138:141], v[188:191], v[106:109]
	v_mfma_f32_16x16x32_bf16 v[94:97], v[130:133], v[200:203], v[94:97]
	v_mfma_f32_16x16x32_bf16 v[90:93], v[138:141], v[200:203], v[90:93]
	v_mfma_f32_16x16x32_bf16 v[82:85], v[130:133], v[208:211], v[82:85]
	v_mfma_f32_16x16x32_bf16 v[74:77], v[138:141], v[208:211], v[74:77]
	v_mfma_f32_16x16x32_bf16 v[126:129], v[134:137], v[184:187], v[126:129]
	v_mfma_f32_16x16x32_bf16 v[122:125], v[142:145], v[184:187], v[122:125]
	v_mfma_f32_16x16x32_bf16 v[110:113], v[134:137], v[196:199], v[110:113]
	v_mfma_f32_16x16x32_bf16 v[106:109], v[142:145], v[196:199], v[106:109]
	v_mfma_f32_16x16x32_bf16 v[94:97], v[134:137], v[204:207], v[94:97]
	v_mfma_f32_16x16x32_bf16 v[90:93], v[142:145], v[204:207], v[90:93]
	v_mfma_f32_16x16x32_bf16 v[82:85], v[134:137], v[212:215], v[82:85]
	v_mfma_f32_16x16x32_bf16 v[74:77], v[142:145], v[212:215], v[74:77]
	s_setprio 0
	s_setprio 1
	v_mfma_f32_16x16x32_bf16 v[118:121], v[146:149], v[180:183], v[118:121]
	v_mfma_f32_16x16x32_bf16 v[114:117], v[154:157], v[180:183], v[114:117]
	v_mfma_f32_16x16x32_bf16 v[102:105], v[146:149], v[188:191], v[102:105]
	v_mfma_f32_16x16x32_bf16 v[98:101], v[154:157], v[188:191], v[98:101]
	v_mfma_f32_16x16x32_bf16 v[86:89], v[146:149], v[200:203], v[86:89]
	v_mfma_f32_16x16x32_bf16 v[78:81], v[154:157], v[200:203], v[78:81]
	v_mfma_f32_16x16x32_bf16 v[70:73], v[146:149], v[208:211], v[70:73]
	v_mfma_f32_16x16x32_bf16 v[66:69], v[154:157], v[208:211], v[66:69]
	v_mfma_f32_16x16x32_bf16 v[118:121], v[150:153], v[184:187], v[118:121]
	v_mfma_f32_16x16x32_bf16 v[114:117], v[158:161], v[184:187], v[114:117]
	v_mfma_f32_16x16x32_bf16 v[102:105], v[150:153], v[196:199], v[102:105]
	v_mfma_f32_16x16x32_bf16 v[98:101], v[158:161], v[196:199], v[98:101]
	v_mfma_f32_16x16x32_bf16 v[86:89], v[150:153], v[204:207], v[86:89]
	v_mfma_f32_16x16x32_bf16 v[78:81], v[158:161], v[204:207], v[78:81]
	v_mfma_f32_16x16x32_bf16 v[70:73], v[150:153], v[212:215], v[70:73]
	v_mfma_f32_16x16x32_bf16 v[66:69], v[158:161], v[212:215], v[66:69]
	s_setprio 0
	s_barrier
	s_add_i32 s53, s53, s7
	s_mov_b32 m0, s53
	ds_read_b128 v[180:183], v179 offset:16384
	ds_read_b128 v[184:187], v179 offset:17408
	ds_read_b128 v[188:191], v179 offset:18432
	ds_read_b128 v[196:199], v179 offset:19456
	ds_read_b128 v[200:203], v179 offset:20480
	ds_read_b128 v[204:207], v179 offset:21504
	ds_read_b128 v[208:211], v179 offset:22528
	ds_read_b128 v[212:215], v179 offset:23552
	global_load_lds_dwordx4 v0, s[44:45]
	s_add_i32 m0, s53, 0x2000
	s_add_u32 s60, s44, 0x80000
	s_addc_u32 s61, s45, 0
	s_add_i32 s53, s66, s7
	global_load_lds_dwordx4 v162, s[44:45]
	s_mov_b32 m0, s53
	s_nop 0
	global_load_lds_dwordx4 v0, s[60:61]
	s_add_i32 m0, s53, 0x2000
	s_nop 0
	global_load_lds_dwordx4 v162, s[60:61]
	s_mov_b32 m0, s11
	s_nop 0
	global_load_lds_dwordx4 v166, s[46:47]
	s_mov_b32 m0, s16
	s_nop 0
	global_load_lds_dwordx4 v164, s[46:47]
	s_waitcnt vmcnt(8)
	s_waitcnt lgkmcnt(0)
	s_barrier
	s_setprio 1
	s_waitcnt lgkmcnt(0)
	v_mfma_f32_16x16x32_bf16 v[62:65], v[130:133], v[180:183], v[62:65]
	v_mfma_f32_16x16x32_bf16 v[58:61], v[138:141], v[180:183], v[58:61]
	v_mfma_f32_16x16x32_bf16 v[46:49], v[130:133], v[188:191], v[46:49]
	v_mfma_f32_16x16x32_bf16 v[42:45], v[138:141], v[188:191], v[42:45]
	v_mfma_f32_16x16x32_bf16 v[34:37], v[130:133], v[200:203], v[34:37]
	v_mfma_f32_16x16x32_bf16 v[26:29], v[138:141], v[200:203], v[26:29]
	v_mfma_f32_16x16x32_bf16 v[18:21], v[130:133], v[208:211], v[18:21]
	v_mfma_f32_16x16x32_bf16 v[10:13], v[138:141], v[208:211], v[10:13]
	v_mfma_f32_16x16x32_bf16 v[62:65], v[134:137], v[184:187], v[62:65]
	v_mfma_f32_16x16x32_bf16 v[58:61], v[142:145], v[184:187], v[58:61]
	v_mfma_f32_16x16x32_bf16 v[46:49], v[134:137], v[196:199], v[46:49]
	v_mfma_f32_16x16x32_bf16 v[42:45], v[142:145], v[196:199], v[42:45]
	v_mfma_f32_16x16x32_bf16 v[34:37], v[134:137], v[204:207], v[34:37]
	v_mfma_f32_16x16x32_bf16 v[26:29], v[142:145], v[204:207], v[26:29]
	v_mfma_f32_16x16x32_bf16 v[18:21], v[134:137], v[212:215], v[18:21]
	v_mfma_f32_16x16x32_bf16 v[10:13], v[142:145], v[212:215], v[10:13]
	s_setprio 0
	s_setprio 1
	v_mfma_f32_16x16x32_bf16 v[54:57], v[146:149], v[180:183], v[54:57]
	v_mfma_f32_16x16x32_bf16 v[50:53], v[154:157], v[180:183], v[50:53]
	v_mfma_f32_16x16x32_bf16 v[38:41], v[146:149], v[188:191], v[38:41]
	v_mfma_f32_16x16x32_bf16 v[30:33], v[154:157], v[188:191], v[30:33]
	v_mfma_f32_16x16x32_bf16 v[22:25], v[146:149], v[200:203], v[22:25]
	v_mfma_f32_16x16x32_bf16 v[14:17], v[154:157], v[200:203], v[14:17]
	v_mfma_f32_16x16x32_bf16 v[6:9], v[146:149], v[208:211], v[6:9]
	v_mfma_f32_16x16x32_bf16 v[2:5], v[154:157], v[208:211], v[2:5]
	v_mfma_f32_16x16x32_bf16 v[54:57], v[150:153], v[184:187], v[54:57]
	v_mfma_f32_16x16x32_bf16 v[50:53], v[158:161], v[184:187], v[50:53]
	v_mfma_f32_16x16x32_bf16 v[38:41], v[150:153], v[196:199], v[38:41]
	v_mfma_f32_16x16x32_bf16 v[30:33], v[158:161], v[196:199], v[30:33]
	v_mfma_f32_16x16x32_bf16 v[22:25], v[150:153], v[204:207], v[22:25]
	v_mfma_f32_16x16x32_bf16 v[14:17], v[158:161], v[204:207], v[14:17]
	v_mfma_f32_16x16x32_bf16 v[6:9], v[150:153], v[212:215], v[6:9]
	v_mfma_f32_16x16x32_bf16 v[2:5], v[158:161], v[212:215], v[2:5]
	s_setprio 0
	s_barrier
; #define PG8_STAGE(bufoff, gbase, voff) do { _Pragma("unroll") for (int _i = 0; _i < 2; ++_i) \
;         __builtin_amdgcn_global_load_lds((const unsigned*)((const char*)(gbase) + (voff)[_i]), (PG8_LAS unsigned*)(lds + (bufoff) + ldsw + _i * 8192), 16, 0, 0); } while (0)
; #define PG8_LDA(dst, b, h) do { _Pragma("unroll") for (int m = 0; m < 4; ++m) _Pragma("unroll") for (int k = 0; k < 2; ++k) dst[m][k] = *(const PG8_LAS bf16x8*)(lds + PG8_SA(b, h) + aoff + m * 2048 + k * 1024); } while (0)
; #define PG8_LDB(dst, b, h) do { _Pragma("unroll") for (int n = 0; n < 2; ++n) _Pragma("unroll") for (int k = 0; k < 2; ++k) dst[n][k] = *(const PG8_LAS bf16x8*)(lds + PG8_SB(b, h) + boff + n * 2048 + k * 1024); } while (0)
; #define PG8_MMA(ai, bj, At, Bt) do { __builtin_amdgcn_s_setprio(1); _Pragma("unroll") for (int m = 0; m < 4; ++m) _Pragma("unroll") for (int n = 0; n < 2; ++n) _Pragma("unroll") for (int k = 0; k < 2; ++k) \
;         acc[ai][bj][m][n] = __builtin_amdgcn_mfma_f32_16x16x32_bf16(Bt[n][k], At[m][k], acc[ai][bj][m][n], 0, 0, 0); __builtin_amdgcn_s_setprio(0); } while (0)
; #define PG8_WAIT_V(n) asm volatile("s_waitcnt vmcnt(" #n ")" ::: "memory")
; #define PG8_WAIT_L(n) asm volatile("s_waitcnt lgkmcnt(" #n ")" ::: "memory")
; #define PG8_BAR __builtin_amdgcn_s_barrier()
; #define PG8_SCHED __builtin_amdgcn_sched_barrier(0)
; template <class Epi, class Sched, bool ALIGN_EPI = false, bool SP2 = false>
; __device__ __forceinline__ void gemm_phase(PG8_LAS unsigned char* lds, const Sched& S, const Epi& E, int wave_id) {
;     ...
;             PG8_LDB(B0, 1, 0); PG8_LDB(B1, 1, 1); PG8_SCHED; PG8_LDA(At, 1, 0); PG8_STAGE(PG8_SA(0, 1), a2 + hstep, voffA);
;             PG8_WAIT_V(8); PG8_WAIT_L(0); PG8_BAR; PG8_MMA(0, 0, At, B0); PG8_MMA(0, 1, At, B1); PG8_BAR; PG8_SCHED;
;             PG8_LDA(At, 1, 1); PG8_STAGE(PG8_SB(1, 0), b3, voffB); PG8_STAGE(PG8_SB(1, 1), b3 + hstep, voffB); PG8_STAGE(PG8_SA(1, 0), a3, voffA);
;             PG8_WAIT_V(8); PG8_WAIT_L(0); PG8_BAR; PG8_MMA(1, 0, At, B0); PG8_MMA(1, 1, At, B1); PG8_BAR; PG8_SCHED;
	s_add_i32 s53, 0, 0x18000
	s_add_i32 s60, 0, 0x1c000
	v_add_u32_e32 v142, s53, v178
	v_add_u32_e32 v158, s60, v178
	ds_read_b128 v[130:133], v142
	ds_read_b128 v[134:137], v142 offset:1024
	ds_read_b128 v[138:141], v142 offset:2048
	ds_read_b128 v[142:145], v142 offset:3072
	ds_read_b128 v[146:149], v158
	ds_read_b128 v[150:153], v158 offset:1024
	ds_read_b128 v[154:157], v158 offset:2048
	ds_read_b128 v[158:161], v158 offset:3072
	s_add_u32 s98, s46, 0x80000
	s_addc_u32 s99, s47, 0
	s_mov_b32 m0, s17
	ds_read_b128 v[180:183], v179 offset:32768
	ds_read_b128 v[184:187], v179 offset:33792
	ds_read_b128 v[188:191], v179 offset:34816
	ds_read_b128 v[196:199], v179 offset:35840
	ds_read_b128 v[200:203], v179 offset:36864
	ds_read_b128 v[204:207], v179 offset:37888
	ds_read_b128 v[208:211], v179 offset:38912
	ds_read_b128 v[212:215], v179 offset:39936
	global_load_lds_dwordx4 v166, s[98:99]
	s_mov_b32 m0, s20
	s_nop 0
	global_load_lds_dwordx4 v164, s[98:99]
	s_waitcnt vmcnt(8)
	s_waitcnt lgkmcnt(0)
	s_barrier
	s_setprio 1
	s_waitcnt lgkmcnt(0)
	v_mfma_f32_16x16x32_bf16 v[126:129], v[130:133], v[180:183], v[126:129]
	v_mfma_f32_16x16x32_bf16 v[122:125], v[138:141], v[180:183], v[122:125]
	v_mfma_f32_16x16x32_bf16 v[110:113], v[130:133], v[188:191], v[110:113]
	v_mfma_f32_16x16x32_bf16 v[106:109], v[138:141], v[188:191], v[106:109]
	v_mfma_f32_16x16x32_bf16 v[94:97], v[130:133], v[200:203], v[94:97]
	v_mfma_f32_16x16x32_bf16 v[90:93], v[138:141], v[200:203], v[90:93]
	v_mfma_f32_16x16x32_bf16 v[82:85], v[130:133], v[208:211], v[82:85]
	v_mfma_f32_16x16x32_bf16 v[74:77], v[138:141], v[208:211], v[74:77]
	v_mfma_f32_16x16x32_bf16 v[126:129], v[134:137], v[184:187], v[126:129]
	v_mfma_f32_16x16x32_bf16 v[122:125], v[142:145], v[184:187], v[122:125]
	v_mfma_f32_16x16x32_bf16 v[110:113], v[134:137], v[196:199], v[110:113]
	v_mfma_f32_16x16x32_bf16 v[106:109], v[142:145], v[196:199], v[106:109]
	v_mfma_f32_16x16x32_bf16 v[94:97], v[134:137], v[204:207], v[94:97]
	v_mfma_f32_16x16x32_bf16 v[90:93], v[142:145], v[204:207], v[90:93]
	v_mfma_f32_16x16x32_bf16 v[82:85], v[134:137], v[212:215], v[82:85]
	v_mfma_f32_16x16x32_bf16 v[74:77], v[142:145], v[212:215], v[74:77]
	s_setprio 0
	s_setprio 1
	v_mfma_f32_16x16x32_bf16 v[118:121], v[146:149], v[180:183], v[118:121]
	v_mfma_f32_16x16x32_bf16 v[114:117], v[154:157], v[180:183], v[114:117]
	v_mfma_f32_16x16x32_bf16 v[102:105], v[146:149], v[188:191], v[102:105]
	v_mfma_f32_16x16x32_bf16 v[98:101], v[154:157], v[188:191], v[98:101]
	v_mfma_f32_16x16x32_bf16 v[86:89], v[146:149], v[200:203], v[86:89]
	v_mfma_f32_16x16x32_bf16 v[78:81], v[154:157], v[200:203], v[78:81]
	v_mfma_f32_16x16x32_bf16 v[70:73], v[146:149], v[208:211], v[70:73]
	v_mfma_f32_16x16x32_bf16 v[66:69], v[154:157], v[208:211], v[66:69]
	v_mfma_f32_16x16x32_bf16 v[118:121], v[150:153], v[184:187], v[118:121]
	v_mfma_f32_16x16x32_bf16 v[114:117], v[158:161], v[184:187], v[114:117]
	v_mfma_f32_16x16x32_bf16 v[102:105], v[150:153], v[196:199], v[102:105]
	v_mfma_f32_16x16x32_bf16 v[98:101], v[158:161], v[196:199], v[98:101]
	v_mfma_f32_16x16x32_bf16 v[86:89], v[150:153], v[204:207], v[86:89]
	v_mfma_f32_16x16x32_bf16 v[78:81], v[158:161], v[204:207], v[78:81]
	v_mfma_f32_16x16x32_bf16 v[70:73], v[150:153], v[212:215], v[70:73]
	v_mfma_f32_16x16x32_bf16 v[66:69], v[158:161], v[212:215], v[66:69]
	s_setprio 0
	s_barrier
	s_add_i32 s100, s53, s7
	s_sub_i32 m0, s100, 0x80
	ds_read_b128 v[180:183], v179 offset:49152
	ds_read_b128 v[184:187], v179 offset:50176
	ds_read_b128 v[188:191], v179 offset:51200
	ds_read_b128 v[196:199], v179 offset:52224
	ds_read_b128 v[200:203], v179 offset:53248
	ds_read_b128 v[204:207], v179 offset:54272
	ds_read_b128 v[208:211], v179 offset:55296
	ds_read_b128 v[212:215], v179 offset:56320
	global_load_lds_dwordx4 v0, s[44:45] offset:128
	s_add_i32 m0, s100, 0x1f80
	s_add_i32 s100, s60, s7
	global_load_lds_dwordx4 v162, s[44:45] offset:128
	s_add_u32 s44, s44, 0x80080
	s_addc_u32 s45, s45, 0
	s_mov_b32 m0, s100
	s_nop 0
	global_load_lds_dwordx4 v0, s[44:45]
	s_add_i32 m0, s100, 0x2000
	s_nop 0
	global_load_lds_dwordx4 v162, s[44:45]
	s_sub_i32 m0, s23, 0x80
	s_nop 0
	global_load_lds_dwordx4 v166, s[46:47] offset:128
	s_sub_i32 m0, s24, 0x80
	s_nop 0
	global_load_lds_dwordx4 v164, s[46:47] offset:128
	s_waitcnt vmcnt(8)
	s_waitcnt lgkmcnt(0)
	s_barrier
	s_setprio 1
	s_waitcnt lgkmcnt(0)
	v_mfma_f32_16x16x32_bf16 v[62:65], v[130:133], v[180:183], v[62:65]
	v_mfma_f32_16x16x32_bf16 v[58:61], v[138:141], v[180:183], v[58:61]
	v_mfma_f32_16x16x32_bf16 v[46:49], v[130:133], v[188:191], v[46:49]
	v_mfma_f32_16x16x32_bf16 v[42:45], v[138:141], v[188:191], v[42:45]
	v_mfma_f32_16x16x32_bf16 v[34:37], v[130:133], v[200:203], v[34:37]
	v_mfma_f32_16x16x32_bf16 v[26:29], v[138:141], v[200:203], v[26:29]
	v_mfma_f32_16x16x32_bf16 v[18:21], v[130:133], v[208:211], v[18:21]
	v_mfma_f32_16x16x32_bf16 v[10:13], v[138:141], v[208:211], v[10:13]
	v_mfma_f32_16x16x32_bf16 v[62:65], v[134:137], v[184:187], v[62:65]
	v_mfma_f32_16x16x32_bf16 v[58:61], v[142:145], v[184:187], v[58:61]
	v_mfma_f32_16x16x32_bf16 v[46:49], v[134:137], v[196:199], v[46:49]
	v_mfma_f32_16x16x32_bf16 v[42:45], v[142:145], v[196:199], v[42:45]
	v_mfma_f32_16x16x32_bf16 v[34:37], v[134:137], v[204:207], v[34:37]
	v_mfma_f32_16x16x32_bf16 v[26:29], v[142:145], v[204:207], v[26:29]
	v_mfma_f32_16x16x32_bf16 v[18:21], v[134:137], v[212:215], v[18:21]
	v_mfma_f32_16x16x32_bf16 v[10:13], v[142:145], v[212:215], v[10:13]
	s_setprio 0
	s_setprio 1
	v_mfma_f32_16x16x32_bf16 v[54:57], v[146:149], v[180:183], v[54:57]
	v_mfma_f32_16x16x32_bf16 v[50:53], v[154:157], v[180:183], v[50:53]
	v_mfma_f32_16x16x32_bf16 v[38:41], v[146:149], v[188:191], v[38:41]
	v_mfma_f32_16x16x32_bf16 v[30:33], v[154:157], v[188:191], v[30:33]
	v_mfma_f32_16x16x32_bf16 v[22:25], v[146:149], v[200:203], v[22:25]
	v_mfma_f32_16x16x32_bf16 v[14:17], v[154:157], v[200:203], v[14:17]
	v_mfma_f32_16x16x32_bf16 v[6:9], v[146:149], v[208:211], v[6:9]
	v_mfma_f32_16x16x32_bf16 v[2:5], v[154:157], v[208:211], v[2:5]
	v_mfma_f32_16x16x32_bf16 v[54:57], v[150:153], v[184:187], v[54:57]
	v_mfma_f32_16x16x32_bf16 v[50:53], v[158:161], v[184:187], v[50:53]
	v_mfma_f32_16x16x32_bf16 v[38:41], v[150:153], v[196:199], v[38:41]
	v_mfma_f32_16x16x32_bf16 v[30:33], v[158:161], v[196:199], v[30:33]
	v_mfma_f32_16x16x32_bf16 v[22:25], v[150:153], v[204:207], v[22:25]
	v_mfma_f32_16x16x32_bf16 v[14:17], v[158:161], v[204:207], v[14:17]
	v_mfma_f32_16x16x32_bf16 v[6:9], v[150:153], v[212:215], v[6:9]
	v_mfma_f32_16x16x32_bf16 v[2:5], v[158:161], v[212:215], v[2:5]
	s_setprio 0
	s_barrier
	s_add_i32 s51, s51, 2
	s_add_u32 s42, s42, 0x100
	s_addc_u32 s43, s43, 0
	s_add_u32 s19, s19, 0x100
	s_addc_u32 s50, s50, 0
	s_cmp_gt_u32 s51, 29
	s_cbranch_scc0 .LBB0_1039
	s_and_b64 vcc, exec, s[12:13]
	s_cbranch_vccz .LBB0_1042
	s_barrier

; __global__ void __launch_bounds__(512, 2) hybrid_fwd(Args a_unused) {
	.amdhsa_kernel _Z10hybrid_fwd4Args
		.amdhsa_group_segment_fixed_size 0
		.amdhsa_private_segment_fixed_size 0
		.amdhsa_kernarg_size 352
		.amdhsa_user_sgpr_count 2
		.amdhsa_user_sgpr_dispatch_ptr 0
		.amdhsa_user_sgpr_queue_ptr 0
		.amdhsa_user_sgpr_kernarg_segment_ptr 1
		.amdhsa_user_sgpr_dispatch_id 0
		.amdhsa_user_sgpr_kernarg_preload_length 0
		.amdhsa_user_sgpr_kernarg_preload_offset 0
		.amdhsa_user_sgpr_private_segment_size 0
		.amdhsa_uses_dynamic_stack 0
		.amdhsa_enable_private_segment 0
		.amdhsa_system_sgpr_workgroup_id_x 1
		.amdhsa_system_sgpr_workgroup_id_y 0
		.amdhsa_system_sgpr_workgroup_id_z 0
		.amdhsa_system_sgpr_workgroup_info 0
		.amdhsa_system_vgpr_workitem_id 2
		.amdhsa_next_free_vgpr 255
		.amdhsa_next_free_sgpr 101
		.amdhsa_accum_offset 256
		.amdhsa_reserve_vcc 1
		.amdhsa_float_round_mode_32 0
		.amdhsa_float_round_mode_16_64 0
		.amdhsa_float_denorm_mode_32 3
		.amdhsa_float_denorm_mode_16_64 3
		.amdhsa_dx10_clamp 1
		.amdhsa_ieee_mode 1
		.amdhsa_fp16_overflow 0
		.amdhsa_tg_split 0
		.amdhsa_exception_fp_ieee_invalid_op 0
		.amdhsa_exception_fp_denorm_src 0
		.amdhsa_exception_fp_ieee_div_zero 0
		.amdhsa_exception_fp_ieee_overflow 0
		.amdhsa_exception_fp_ieee_underflow 0
		.amdhsa_exception_fp_ieee_inexact 0
		.amdhsa_exception_int_div_zero 0
	.end_amdhsa_kernel

; __global__ void __launch_bounds__(512, 2) hybrid_fwd(Args a_unused) {
amdhsa.kernels:
  - .agpr_count:     0
    .args:
      - .offset:         0
        .size:           96
        .value_kind:     by_value
      - .offset:         96
        .size:           4
        .value_kind:     hidden_block_count_x
      - .offset:         100
        .size:           4
        .value_kind:     hidden_block_count_y
      - .offset:         104
        .size:           4
        .value_kind:     hidden_block_count_z
      - .offset:         108
        .size:           2
        .value_kind:     hidden_group_size_x
      - .offset:         110
        .size:           2
        .value_kind:     hidden_group_size_y
      - .offset:         112
        .size:           2
        .value_kind:     hidden_group_size_z
      - .offset:         114
        .size:           2
        .value_kind:     hidden_remainder_x
      - .offset:         116
        .size:           2
        .value_kind:     hidden_remainder_y
      - .offset:         118
        .size:           2
        .value_kind:     hidden_remainder_z
      - .offset:         136
        .size:           8
        .value_kind:     hidden_global_offset_x
      - .offset:         144
        .size:           8
        .value_kind:     hidden_global_offset_y
      - .offset:         152
        .size:           8
        .value_kind:     hidden_global_offset_z
      - .offset:         160
        .size:           2
        .value_kind:     hidden_grid_dims
      - .offset:         184
        .size:           8
        .value_kind:     hidden_multigrid_sync_arg
      - .offset:         216
        .size:           4
        .value_kind:     hidden_dynamic_lds_size
    .group_segment_fixed_size: 0
    .kernarg_segment_align: 8
    .kernarg_segment_size: 352
    .language:       OpenCL C
    .language_version:
      - 2
      - 0
    .max_flat_workgroup_size: 512
    .name:           _Z10hybrid_fwd4Args
    .private_segment_fixed_size: 0
    .sgpr_count:     107
    .sgpr_spill_count: 143
    .symbol:         _Z10hybrid_fwd4Args.kd
    .uniform_work_group_size: 1
    .uses_dynamic_stack: false
    .vgpr_count:     255
    .vgpr_spill_count: 0
    .wavefront_size: 64
